# v48 + P5: workgroups with odd (bx>>3) start ~1 us later (spreads epilogue store bursts inside each XCD)
# baseline (speedup 1.0000x reference)
.LBB0_2255:
	s_bitcmp1_b32 s91, 3
	s_cbranch_scc0 .Lp5_nodelay
	s_sleep 23
